# P1 tail: carried-window sums issue all 15 row loads then wait once (was 15 serialised load/wait pairs); P7 epilogue waits
# speedup vs baseline: 1.0045x; 1.0040x over previous
.Lsp_join:
	v_ashrrev_i32_e32 v11, 31, v10
	v_add_u32_e32 v17, s18, v17
	v_lshlrev_b64 v[10:11], 11, v[10:11]
	v_cmp_lt_i32_e32 vcc, s20, v17
	v_lshl_add_u64 v[10:11], v[8:9], 0, v[10:11]
	s_or_b64 s[14:15], vcc, s[14:15]
	global_store_dwordx4 v[10:11], v[2:5], off
	s_andn2_b64 exec, exec, s[14:15]
	s_cbranch_execz .LBB0_197
.LBB0_169:
	v_ashrrev_i32_e32 v10, 7, v17
	v_and_b32_e32 v13, 0x7f, v17
	v_mul_u32_u24_e32 v12, 0x7800, v10
	v_lshl_add_u32 v12, v13, 4, v12
	v_add_u32_e32 v13, 0x1000, v12
	v_add_u32_e32 v14, 0x2000, v12
	v_add_u32_e32 v15, 0x3000, v12
	v_add_u32_e32 v18, 0x4000, v12
	v_add_u32_e32 v19, 0x5000, v12
	v_add_u32_e32 v20, 0x6000, v12
	v_add_u32_e32 v21, 0x7000, v12
	v_and_b32_e32 v11, 0x60, v17
	global_load_dwordx4 v[86:89], v21, s[88:89]
	s_and_saveexec_b64 s[6:7], s[0:1]
	global_load_dwordx4 v[82:85], v20, s[88:89] offset:2048
	global_load_dwordx4 v[78:81], v20, s[88:89]
	s_and_b64 exec, exec, s[4:5]
	global_load_dwordx4 v[74:77], v19, s[88:89] offset:2048
	global_load_dwordx4 v[70:73], v19, s[88:89]
	global_load_dwordx4 v[66:69], v18, s[88:89] offset:2048
	global_load_dwordx4 v[62:65], v18, s[88:89]
	v_cmp_eq_u32_e64 s[16:17], s19, v11
	s_nop 1
	s_and_b64 exec, exec, s[16:17]
	global_load_dwordx4 v[58:61], v15, s[88:89] offset:2048
	global_load_dwordx4 v[54:57], v15, s[88:89]
	global_load_dwordx4 v[50:53], v14, s[88:89] offset:2048
	global_load_dwordx4 v[46:49], v14, s[88:89]
	global_load_dwordx4 v[42:45], v13, s[88:89] offset:2048
	global_load_dwordx4 v[38:41], v13, s[88:89]
	global_load_dwordx4 v[34:37], v12, s[88:89] offset:2048
	global_load_dwordx4 v[30:33], v12, s[88:89]
	s_mov_b64 exec, s[6:7]
	s_waitcnt vmcnt(0)
	v_pk_add_f32 v[4:5], v[88:89], 0 op_sel_hi:[1,0]
	v_pk_add_f32 v[2:3], v[86:87], 0 op_sel_hi:[1,0]
	s_and_b64 exec, exec, s[0:1]
	v_pk_add_f32 v[4:5], v[4:5], v[84:85]
	v_pk_add_f32 v[2:3], v[2:3], v[82:83]
	v_pk_add_f32 v[4:5], v[4:5], v[80:81]
	v_pk_add_f32 v[2:3], v[2:3], v[78:79]
	s_and_b64 exec, exec, s[4:5]
	v_pk_add_f32 v[4:5], v[4:5], v[76:77]
	v_pk_add_f32 v[2:3], v[2:3], v[74:75]
	v_pk_add_f32 v[4:5], v[4:5], v[72:73]
	v_pk_add_f32 v[2:3], v[2:3], v[70:71]
	v_pk_add_f32 v[4:5], v[4:5], v[68:69]
	v_pk_add_f32 v[2:3], v[2:3], v[66:67]
	v_pk_add_f32 v[4:5], v[4:5], v[64:65]
	v_pk_add_f32 v[2:3], v[2:3], v[62:63]
	s_and_b64 exec, exec, s[16:17]
	v_pk_add_f32 v[4:5], v[4:5], v[60:61]
	v_pk_add_f32 v[2:3], v[2:3], v[58:59]
	v_pk_add_f32 v[4:5], v[4:5], v[56:57]
	v_pk_add_f32 v[2:3], v[2:3], v[54:55]
	v_pk_add_f32 v[4:5], v[4:5], v[52:53]
	v_pk_add_f32 v[2:3], v[2:3], v[50:51]
	v_pk_add_f32 v[4:5], v[4:5], v[48:49]
	v_pk_add_f32 v[2:3], v[2:3], v[46:47]
	v_pk_add_f32 v[4:5], v[4:5], v[44:45]
	v_pk_add_f32 v[2:3], v[2:3], v[42:43]
	v_pk_add_f32 v[4:5], v[4:5], v[40:41]
	v_pk_add_f32 v[2:3], v[2:3], v[38:39]
	v_pk_add_f32 v[4:5], v[4:5], v[36:37]
	v_pk_add_f32 v[2:3], v[2:3], v[34:35]
	v_pk_add_f32 v[4:5], v[4:5], v[32:33]
	v_pk_add_f32 v[2:3], v[2:3], v[30:31]
	s_mov_b64 exec, s[6:7]
	s_branch .Lsp_join
